# grid barrier: last XCD leader bumps all per-XCD generation words directly (no relay hop)
# speedup vs baseline: 1.0229x; 1.0063x over previous
.LBB0_198:
	s_or_b64 exec, exec, s[4:5]
	s_and_saveexec_b64 s[4:5], s[8:9]
	s_cbranch_execz .LBB0_200
	v_mov_b32_e32 v2, 1
	global_atomic_add v[0:1], v2, off
	v_readlane_b32 s98, v252, 10
	v_readlane_b32 s99, v252, 11
	v_mov_b32_e32 v3, 0
	s_add_u32 s98, s98, 0x2400
	s_addc_u32 s99, s99, 0
	s_nop 4
	global_atomic_add v3, v2, s[98:99]
	global_atomic_add v3, v2, s[98:99] offset:256
	global_atomic_add v3, v2, s[98:99] offset:512
	global_atomic_add v3, v2, s[98:99] offset:768
	global_atomic_add v3, v2, s[98:99] offset:1024
	global_atomic_add v3, v2, s[98:99] offset:1280
	global_atomic_add v3, v2, s[98:99] offset:1536
	global_atomic_add v3, v2, s[98:99] offset:1792
	global_atomic_add v3, v2, s[98:99] offset:2048
	global_atomic_add v3, v2, s[98:99] offset:2304
	global_atomic_add v3, v2, s[98:99] offset:2560
	global_atomic_add v3, v2, s[98:99] offset:2816
	global_atomic_add v3, v2, s[98:99] offset:3072
	global_atomic_add v3, v2, s[98:99] offset:3328
	global_atomic_add v3, v2, s[98:99] offset:3584
	global_atomic_add v3, v2, s[98:99] offset:3840
.LBB0_200:
	s_or_b64 exec, exec, s[4:5]
	s_mov_b64 s[4:5], exec
	v_mbcnt_lo_u32_b32 v0, s4, 0
	v_mbcnt_hi_u32_b32 v0, s5, v0
	v_cmp_eq_u32_e32 vcc, 0, v0
	s_waitcnt vmcnt(0)
	buffer_inv sc1
	s_and_saveexec_b64 s[6:7], vcc
	s_cbranch_execz .LBB0_202
	s_bcnt1_i32_b64 s4, s[4:5]
	v_mov_b32_e32 v0, 0x2000
	v_mov_b32_e32 v1, s4


.LBB0_283:
	s_or_b64 exec, exec, s[4:5]
	s_and_saveexec_b64 s[4:5], s[6:7]
	s_cbranch_execz .LBB0_285
	global_atomic_add v[2:3], v197, off
	v_readlane_b32 s98, v252, 10
	v_readlane_b32 s99, v252, 11
	v_mov_b32_e32 v0, 0
	s_add_u32 s98, s98, 0x2400
	s_addc_u32 s99, s99, 0
	s_nop 4
	global_atomic_add v0, v197, s[98:99]
	global_atomic_add v0, v197, s[98:99] offset:256
	global_atomic_add v0, v197, s[98:99] offset:512
	global_atomic_add v0, v197, s[98:99] offset:768
	global_atomic_add v0, v197, s[98:99] offset:1024
	global_atomic_add v0, v197, s[98:99] offset:1280
	global_atomic_add v0, v197, s[98:99] offset:1536
	global_atomic_add v0, v197, s[98:99] offset:1792
	global_atomic_add v0, v197, s[98:99] offset:2048
	global_atomic_add v0, v197, s[98:99] offset:2304
	global_atomic_add v0, v197, s[98:99] offset:2560
	global_atomic_add v0, v197, s[98:99] offset:2816
	global_atomic_add v0, v197, s[98:99] offset:3072
	global_atomic_add v0, v197, s[98:99] offset:3328
	global_atomic_add v0, v197, s[98:99] offset:3584
	global_atomic_add v0, v197, s[98:99] offset:3840
.LBB0_285:
	s_or_b64 exec, exec, s[4:5]
	s_mov_b64 s[4:5], exec
	v_mbcnt_lo_u32_b32 v0, s4, 0
	v_mbcnt_hi_u32_b32 v0, s5, v0
	v_cmp_eq_u32_e32 vcc, 0, v0
	s_waitcnt vmcnt(0)
	buffer_inv sc1
	s_and_saveexec_b64 s[6:7], vcc
	s_cbranch_execz .LBB0_287
	s_bcnt1_i32_b64 s4, s[4:5]
	v_mov_b32_e32 v0, s4


.LBB0_1033:
	s_or_b64 exec, exec, s[4:5]
	s_and_saveexec_b64 s[4:5], s[18:19]
	s_cbranch_execz .LBB0_1035
	global_atomic_add v[2:3], v197, off
	v_readlane_b32 s98, v252, 10
	v_readlane_b32 s99, v252, 11
	v_mov_b32_e32 v0, 0
	s_add_u32 s98, s98, 0x2400
	s_addc_u32 s99, s99, 0
	s_nop 4
	global_atomic_add v0, v197, s[98:99]
	global_atomic_add v0, v197, s[98:99] offset:256
	global_atomic_add v0, v197, s[98:99] offset:512
	global_atomic_add v0, v197, s[98:99] offset:768
	global_atomic_add v0, v197, s[98:99] offset:1024
	global_atomic_add v0, v197, s[98:99] offset:1280
	global_atomic_add v0, v197, s[98:99] offset:1536
	global_atomic_add v0, v197, s[98:99] offset:1792
	global_atomic_add v0, v197, s[98:99] offset:2048
	global_atomic_add v0, v197, s[98:99] offset:2304
	global_atomic_add v0, v197, s[98:99] offset:2560
	global_atomic_add v0, v197, s[98:99] offset:2816
	global_atomic_add v0, v197, s[98:99] offset:3072
	global_atomic_add v0, v197, s[98:99] offset:3328
	global_atomic_add v0, v197, s[98:99] offset:3584
	global_atomic_add v0, v197, s[98:99] offset:3840
.LBB0_1035:
	s_or_b64 exec, exec, s[4:5]
	s_mov_b64 s[4:5], exec
	v_mbcnt_lo_u32_b32 v0, s4, 0
	v_mbcnt_hi_u32_b32 v0, s5, v0
	v_cmp_eq_u32_e32 vcc, 0, v0
	s_waitcnt vmcnt(0)
	buffer_inv sc1
	s_and_saveexec_b64 s[18:19], vcc
	s_cbranch_execz .LBB0_1037
	s_bcnt1_i32_b64 s4, s[4:5]
	v_mov_b32_e32 v0, s4


.LBB0_1170:
	s_or_b64 exec, exec, s[4:5]
	s_mov_b64 s[4:5], exec
	v_mbcnt_lo_u32_b32 v0, s4, 0
	v_mbcnt_hi_u32_b32 v0, s5, v0
	v_cmp_eq_u32_e32 vcc, 0, v0
	s_waitcnt vmcnt(0)
	buffer_inv sc1
	s_and_saveexec_b64 s[6:7], vcc
	s_cbranch_execz .LBB0_204
	s_bcnt1_i32_b64 s4, s[4:5]
	v_mov_b32_e32 v0, s4

	s_branch .LBB0_204
